# norm1 tiles: all 20 loads issued up front as in norm2
# baseline (speedup 1.0000x reference)
.LBB0_138:
	v_min_i32_e32 v0, 0x4000, v18
	v_ashrrev_i32_e32 v0, 12, v0
	v_lshlrev_b64 v[4:5], 12, v[4:5]
	v_and_b32_e32 v64, 63, v6
	v_add_u32_e32 v0, s66, v0
	v_mov_b64_e32 v[6:7], s[90:91]
	v_lshl_add_u64 v[2:3], v[2:3], 0, v[4:5]
	v_mad_i64_i32 v[6:7], s[0:1], v0, s68, v[6:7]
	v_lshlrev_b32_e32 v0, 4, v64
	v_lshl_add_u64 v[4:5], v[2:3], 0, s[64:65]
	v_lshl_add_u64 v[20:21], v[2:3], 0, v[0:1]
	v_or_b32_e32 v2, 0x400, v0
	v_mov_b32_e32 v3, v1
	v_or_b32_e32 v8, 0x800, v0
	v_mov_b32_e32 v9, v1
	v_or_b32_e32 v10, 0xc00, v0
	v_mov_b32_e32 v11, v1
	v_lshl_add_u64 v[24:25], v[4:5], 0, v[0:1]
	v_lshl_add_u64 v[22:23], v[4:5], 0, v[2:3]
	v_lshl_add_u64 v[14:15], v[4:5], 0, v[8:9]
	v_lshl_add_u64 v[26:27], v[4:5], 0, v[10:11]
	v_lshl_add_u64 v[4:5], v[6:7], 0, s[64:65]
	v_lshl_add_u64 v[38:39], v[4:5], 0, v[0:1]
	v_lshl_add_u64 v[50:51], v[4:5], 0, v[2:3]
	v_lshl_add_u64 v[44:45], v[4:5], 0, v[8:9]
	v_lshl_add_u64 v[40:41], v[4:5], 0, v[10:11]
	v_readlane_b32 s48, v210, 50
	v_readlane_b32 s50, v210, 52
	v_readlane_b32 s51, v210, 53
	v_readlane_b32 s60, v210, 62
	v_readlane_b32 s61, v210, 63
	v_readlane_b32 s62, v209, 0
	v_readlane_b32 s63, v209, 1
	v_readlane_b32 s56, v210, 58
	v_readlane_b32 s57, v210, 59
	v_readlane_b32 s58, v210, 60
	v_readlane_b32 s60, v209, 3
	v_readlane_b32 s64, v209, 7
	v_readlane_b32 s65, v209, 8
	v_readlane_b32 s66, v209, 9
	v_readlane_b32 s49, v210, 51
	v_readlane_b32 s52, v210, 54
	v_readlane_b32 s53, v210, 55
	v_readlane_b32 s54, v210, 56
	v_readlane_b32 s55, v210, 57
	v_readlane_b32 s59, v210, 61
	v_readlane_b32 s61, v209, 4
	v_readlane_b32 s62, v209, 5
	v_readlane_b32 s63, v209, 6
	v_readlane_b32 s67, v209, 10
	v_lshl_add_u64 v[42:43], v[6:7], 0, v[0:1]
	v_ashrrev_i32_e32 v19, 31, v18
	v_lshlrev_b64 v[18:19], 11, v[18:19]
	v_lshl_add_u64 v[56:57], s[50:51], 0, v[18:19]
	s_mov_b32 s56, 0x10000
	s_mov_b32 s57, 0x20000
	s_mov_b32 s58, 0x30000
	v_lshlrev_b32_e32 v58, 3, v64
	v_mov_b32_e32 v59, v1
	v_lshl_add_u64 v[58:59], v[56:57], 0, v[58:59]
	global_load_dwordx4 v[72:75], v[20:21], off
	global_load_dwordx4 v[76:79], v[20:21], off offset:1024
	global_load_dwordx4 v[80:83], v[20:21], off offset:2048
	global_load_dwordx4 v[84:87], v[20:21], off offset:3072
	global_load_dwordx4 v[88:91], v[24:25], off
	global_load_dwordx4 v[92:95], v[22:23], off
	global_load_dwordx4 v[96:99], v[14:15], off
	global_load_dwordx4 v[100:103], v[26:27], off
	global_load_dwordx4 v[136:139], v0, s[38:39]
	global_load_dwordx4 v[140:143], v0, s[38:39] offset:1024
	global_load_dwordx4 v[144:147], v0, s[38:39] offset:2048
	global_load_dwordx4 v[148:151], v0, s[38:39] offset:3072
	global_load_dwordx4 v[152:155], v[42:43], off
	global_load_dwordx4 v[156:159], v[42:43], off offset:1024
	global_load_dwordx4 v[160:163], v[42:43], off offset:2048
	global_load_dwordx4 v[164:167], v[42:43], off offset:3072
	global_load_dwordx4 v[184:187], v[38:39], off
	global_load_dwordx4 v[188:191], v[50:51], off
	global_load_dwordx4 v[192:195], v[44:45], off
	global_load_dwordx4 v[196:199], v[40:41], off
	s_waitcnt vmcnt(12)
	v_pk_mul_f32 v[200:201], v[72:73], v[72:73]
	v_pk_fma_f32 v[200:201], v[74:75], v[74:75], v[200:201]
	v_pk_fma_f32 v[200:201], v[76:77], v[76:77], v[200:201]
	v_pk_fma_f32 v[200:201], v[78:79], v[78:79], v[200:201]
	v_pk_fma_f32 v[200:201], v[80:81], v[80:81], v[200:201]
	v_pk_fma_f32 v[200:201], v[82:83], v[82:83], v[200:201]
	v_pk_fma_f32 v[200:201], v[84:85], v[84:85], v[200:201]
	v_pk_fma_f32 v[200:201], v[86:87], v[86:87], v[200:201]
	v_pk_mul_f32 v[202:203], v[88:89], v[88:89]
	v_pk_fma_f32 v[202:203], v[90:91], v[90:91], v[202:203]
	v_pk_fma_f32 v[202:203], v[92:93], v[92:93], v[202:203]
	v_pk_fma_f32 v[202:203], v[94:95], v[94:95], v[202:203]
	v_pk_fma_f32 v[202:203], v[96:97], v[96:97], v[202:203]
	v_pk_fma_f32 v[202:203], v[98:99], v[98:99], v[202:203]
	v_pk_fma_f32 v[202:203], v[100:101], v[100:101], v[202:203]
	v_pk_fma_f32 v[202:203], v[102:103], v[102:103], v[202:203]
	v_add_f32_e32 v200, v200, v201
	v_add_f32_e32 v202, v202, v203
	s_nop 0
	v_add_f32_dpp v200, v200, v200 quad_perm:[1,0,3,2] row_mask:0xf bank_mask:0xf bound_ctrl:1
	v_add_f32_dpp v202, v202, v202 quad_perm:[1,0,3,2] row_mask:0xf bank_mask:0xf bound_ctrl:1
	s_nop 0
	v_add_f32_dpp v200, v200, v200 quad_perm:[2,3,0,1] row_mask:0xf bank_mask:0xf bound_ctrl:1
	v_add_f32_dpp v202, v202, v202 quad_perm:[2,3,0,1] row_mask:0xf bank_mask:0xf bound_ctrl:1
	s_nop 0
	v_add_f32_dpp v200, v200, v200 row_half_mirror row_mask:0xf bank_mask:0xf bound_ctrl:1
	v_add_f32_dpp v202, v202, v202 row_half_mirror row_mask:0xf bank_mask:0xf bound_ctrl:1
	s_nop 0
	v_add_f32_dpp v200, v200, v200 row_mirror row_mask:0xf bank_mask:0xf bound_ctrl:1
	v_add_f32_dpp v202, v202, v202 row_mirror row_mask:0xf bank_mask:0xf bound_ctrl:1
	s_nop 0
	v_add_f32_dpp v200, v200, v200 row_bcast:15 row_mask:0xa bank_mask:0xf
	v_add_f32_dpp v202, v202, v202 row_bcast:15 row_mask:0xa bank_mask:0xf
	s_nop 0
	v_add_f32_dpp v200, v200, v200 row_bcast:31 row_mask:0xc bank_mask:0xf
	v_add_f32_dpp v202, v202, v202 row_bcast:31 row_mask:0xc bank_mask:0xf
	s_nop 0
	s_nop 1
	v_readlane_b32 s0, v200, 63
	v_readlane_b32 s1, v202, 63
	v_mov_b32_e32 v204, s0
	v_mov_b32_e32 v168, s1
	v_fma_f32 v204, v204, s10, v132
	v_fma_f32 v168, v168, s10, v132
	v_rsq_f32_e32 v204, v204
	v_rsq_f32_e32 v168, v168
	s_nop 0
	v_mov_b32_e32 v205, v204
	v_mov_b32_e32 v169, v168
	s_waitcnt vmcnt(0)
	v_pk_add_f32 v[184:185], v[184:185], 1.0 op_sel_hi:[1,0]
	v_pk_add_f32 v[186:187], v[186:187], 1.0 op_sel_hi:[1,0]
	v_pk_add_f32 v[188:189], v[188:189], 1.0 op_sel_hi:[1,0]
	v_pk_add_f32 v[190:191], v[190:191], 1.0 op_sel_hi:[1,0]
	v_pk_add_f32 v[192:193], v[192:193], 1.0 op_sel_hi:[1,0]
	v_pk_add_f32 v[194:195], v[194:195], 1.0 op_sel_hi:[1,0]
	v_pk_add_f32 v[196:197], v[196:197], 1.0 op_sel_hi:[1,0]
	v_pk_add_f32 v[198:199], v[198:199], 1.0 op_sel_hi:[1,0]
	v_pk_mul_f32 v[72:73], v[72:73], v[204:205]
	v_pk_mul_f32 v[72:73], v[136:137], v[72:73]
	v_pk_fma_f32 v[72:73], v[184:185], v[72:73], v[152:153]
	v_pk_mul_f32 v[74:75], v[74:75], v[204:205]
	v_pk_mul_f32 v[74:75], v[138:139], v[74:75]
	v_pk_fma_f32 v[74:75], v[186:187], v[74:75], v[154:155]
	v_cvt_pk_bf16_f32 v72, v72, v73
	v_cvt_pk_bf16_f32 v73, v74, v75
	global_store_dwordx2 v[58:59], v[72:73], off
	v_pk_mul_f32 v[76:77], v[76:77], v[204:205]
	v_pk_mul_f32 v[76:77], v[140:141], v[76:77]
	v_pk_fma_f32 v[76:77], v[188:189], v[76:77], v[156:157]
	v_pk_mul_f32 v[78:79], v[78:79], v[204:205]
	v_pk_mul_f32 v[78:79], v[142:143], v[78:79]
	v_pk_fma_f32 v[78:79], v[190:191], v[78:79], v[158:159]
	v_cvt_pk_bf16_f32 v76, v76, v77
	v_cvt_pk_bf16_f32 v77, v78, v79
	global_store_dwordx2 v[58:59], v[76:77], off offset:512
	v_pk_mul_f32 v[80:81], v[80:81], v[204:205]
	v_pk_mul_f32 v[80:81], v[144:145], v[80:81]
	v_pk_fma_f32 v[80:81], v[192:193], v[80:81], v[160:161]
	v_pk_mul_f32 v[82:83], v[82:83], v[204:205]
	v_pk_mul_f32 v[82:83], v[146:147], v[82:83]
	v_pk_fma_f32 v[82:83], v[194:195], v[82:83], v[162:163]
	v_cvt_pk_bf16_f32 v80, v80, v81
	v_cvt_pk_bf16_f32 v81, v82, v83
	global_store_dwordx2 v[58:59], v[80:81], off offset:1024
	v_pk_mul_f32 v[84:85], v[84:85], v[204:205]
	v_pk_mul_f32 v[84:85], v[148:149], v[84:85]
	v_pk_fma_f32 v[84:85], v[196:197], v[84:85], v[164:165]
	v_pk_mul_f32 v[86:87], v[86:87], v[204:205]
	v_pk_mul_f32 v[86:87], v[150:151], v[86:87]
	v_pk_fma_f32 v[86:87], v[198:199], v[86:87], v[166:167]
	v_cvt_pk_bf16_f32 v84, v84, v85
	v_cvt_pk_bf16_f32 v85, v86, v87
	global_store_dwordx2 v[58:59], v[84:85], off offset:1536
	v_pk_mul_f32 v[88:89], v[88:89], v[168:169]
	v_pk_mul_f32 v[88:89], v[136:137], v[88:89]
	v_pk_fma_f32 v[88:89], v[184:185], v[88:89], v[152:153]
	v_pk_mul_f32 v[90:91], v[90:91], v[168:169]
	v_pk_mul_f32 v[90:91], v[138:139], v[90:91]
	v_pk_fma_f32 v[90:91], v[186:187], v[90:91], v[154:155]
	v_cvt_pk_bf16_f32 v88, v88, v89
	v_cvt_pk_bf16_f32 v89, v90, v91
	global_store_dwordx2 v[58:59], v[88:89], off offset:2048
	v_pk_mul_f32 v[92:93], v[92:93], v[168:169]
	v_pk_mul_f32 v[92:93], v[140:141], v[92:93]
	v_pk_fma_f32 v[92:93], v[188:189], v[92:93], v[156:157]
	v_pk_mul_f32 v[94:95], v[94:95], v[168:169]
	v_pk_mul_f32 v[94:95], v[142:143], v[94:95]
	v_pk_fma_f32 v[94:95], v[190:191], v[94:95], v[158:159]
	v_cvt_pk_bf16_f32 v92, v92, v93
	v_cvt_pk_bf16_f32 v93, v94, v95
	global_store_dwordx2 v[58:59], v[92:93], off offset:2560
	v_pk_mul_f32 v[96:97], v[96:97], v[168:169]
	v_pk_mul_f32 v[96:97], v[144:145], v[96:97]
	v_pk_fma_f32 v[96:97], v[192:193], v[96:97], v[160:161]
	v_pk_mul_f32 v[98:99], v[98:99], v[168:169]
	v_pk_mul_f32 v[98:99], v[146:147], v[98:99]
	v_pk_fma_f32 v[98:99], v[194:195], v[98:99], v[162:163]
	v_cvt_pk_bf16_f32 v96, v96, v97
	v_cvt_pk_bf16_f32 v97, v98, v99
	global_store_dwordx2 v[58:59], v[96:97], off offset:3072
	v_pk_mul_f32 v[100:101], v[100:101], v[168:169]
	v_pk_mul_f32 v[100:101], v[148:149], v[100:101]
	v_pk_fma_f32 v[100:101], v[196:197], v[100:101], v[164:165]
	v_pk_mul_f32 v[102:103], v[102:103], v[168:169]
	v_pk_mul_f32 v[102:103], v[150:151], v[102:103]
	v_pk_fma_f32 v[102:103], v[198:199], v[102:103], v[166:167]
	v_cvt_pk_bf16_f32 v100, v100, v101
	v_cvt_pk_bf16_f32 v101, v102, v103
	global_store_dwordx2 v[58:59], v[100:101], off offset:3584
	s_mov_b64 s[0:1], 0
